# role B keeps its raised priority through the unit epilogue and header (its epilogue is the unit-transition critical path)
# speedup vs baseline: 1.0010x; 1.0010x over previous
; #define PG8_WAIT_V(n) asm volatile("s_waitcnt vmcnt(" #n ")" ::: "memory")
; #define PG8_BAR __builtin_amdgcn_s_barrier()
; template <class Epi, class Sched, bool ALIGN_EPI>
; __device__ __forceinline__ void gemm_phase(PG8_LAS unsigned char* lds, const Gemm g, const Sched& S, const Epi& E) {
;     ...
;     PG8_WAIT_V(0);
;     if constexpr (!ALIGN_EPI) { if (wr == 0) PG8_BAR; }
;     PG8_BAR;
.LBB0_907:
	s_setprio 0
	s_waitcnt lgkmcnt(0)
	s_waitcnt vmcnt(0)
	s_barrier

; #define PG8_WAIT_V(n) asm volatile("s_waitcnt vmcnt(" #n ")" ::: "memory")
; #define PG8_BAR __builtin_amdgcn_s_barrier()
; template <class Epi, class Sched, bool ALIGN_EPI>
; __device__ __forceinline__ void gemm_phase(PG8_LAS unsigned char* lds, const Gemm g, const Sched& S, const Epi& E) {
;     ...
;     PG8_WAIT_V(0);
;     if constexpr (!ALIGN_EPI) { if (wr == 0) PG8_BAR; }
;     PG8_BAR;
.LBB0_954:
	s_setprio 0
	s_waitcnt vmcnt(0)
	s_barrier
